# extended the 4+4 DMA rebalance and setprio removal to the two fused P9 loops
# speedup vs baseline: 1.0049x; 1.0049x over previous
; #define PG8_STAGE(bufoff, gbase, voff) do { _Pragma("unroll") for (int _i = 0; _i < 2; ++_i) \
;         __builtin_amdgcn_global_load_lds((const unsigned*)((const char*)(gbase) + (voff)[_i]), (PG8_LAS unsigned*)(lds + (bufoff) + ldsw + _i * 8192), 16, 0, 0); } while (0)
; #define PG8_STAGE_NT(bufoff, gbase, voff) do { _Pragma("unroll") for (int _i = 0; _i < 2; ++_i) \
;         __builtin_amdgcn_global_load_lds((const unsigned*)((const char*)(gbase) + (voff)[_i]), (PG8_LAS unsigned*)(lds + (bufoff) + ldsw + _i * 8192), 16, 0, PG8_B_AUX); } while (0)
; #define PG8_LDA(dst, b, h) do { _Pragma("unroll") for (int m = 0; m < 4; ++m) _Pragma("unroll") for (int k = 0; k < 2; ++k) dst[m][k] = *(const PG8_LAS bf16x8*)(lds + PG8_SA(b, h) + aoff + m * 2048 + k * 1024); } while (0)
; #define PG8_LDB(dst, b, h) do { _Pragma("unroll") for (int n = 0; n < 2; ++n) _Pragma("unroll") for (int k = 0; k < 2; ++k) dst[n][k] = *(const PG8_LAS bf16x8*)(lds + PG8_SB(b, h) + boff + n * 2048 + k * 1024); } while (0)
; #define PG8_WAIT_V(n) asm volatile("s_waitcnt vmcnt(" #n ")" ::: "memory")
; #define PG8_WAIT_L(n) asm volatile("s_waitcnt lgkmcnt(" #n ")" ::: "memory")
; #define PG8_BAR __builtin_amdgcn_s_barrier()
; template <class Epi, class Sched, bool ALIGN_EPI = false, bool SP2 = false>
; __device__ __forceinline__ void gemm_phase(PG8_LAS unsigned char* lds, const Gemm g, const Sched& S, const Epi& E, int wid) {
;     ...
;         for (int t = 0; t < nt; t += 2) {
;             const bool last = (t == nt - 2);
;             const char* a1 = cA + (size_t)(t + 1) * kstep;
;             const char* a2 = last ? nA : cA + (size_t)(t + 2) * kstep; const char* b2 = last ? nB : cB + (size_t)(t + 2) * kstep;
;             const char* a3 = a2 + kstep; const char* b3 = b2 + kstep;
;             if (last && has_next) S.a_ready(nxt);
;             if constexpr (SP2) {
;             PG8_LDB(B0, 0, 0); PG8_LDB(B1, 0, 1); PG8_SCHED; PG8_LDA(At, 0, 0); PG8_STAGE(PG8_SA(1, 1), a1 + hstepA, voffA);
;             PG8_WAIT_V(8); PG8_WAIT_L(0); PG8_BAR; PG8_MMA(0, 0, At, B0); PG8_MMA(0, 1, At, B1); PG8_BAR; PG8_SCHED;
;             PG8_LDA(At, 0, 1); PG8_STAGE_NT(PG8_SB(0, 0), b2, voffB); PG8_STAGE_NT(PG8_SB(0, 1), b2 + hstepB, voffB); PG8_STAGE(PG8_SA(0, 0), a2, voffA);
;             PG8_WAIT_V(8); PG8_WAIT_L(0); PG8_BAR; PG8_MMA(1, 0, At, B0); PG8_MMA(1, 1, At, B1); PG8_BAR; PG8_SCHED;
.LBB0_1249:
	ds_read_b128 v[146:149], v141
	ds_read_b128 v[150:153], v141 offset:1024
	ds_read_b128 v[154:157], v141 offset:2048
	ds_read_b128 v[158:161], v141 offset:3072
	ds_read_b128 v[162:165], v142
	ds_read_b128 v[166:169], v142 offset:1024
	ds_read_b128 v[170:173], v142 offset:2048
	ds_read_b128 v[174:177], v142 offset:3072
	s_add_u32 s46, s14, s50
	s_addc_u32 s47, s15, s51
	s_add_u32 s53, s14, s44
	s_addc_u32 s54, s15, s45
	s_cmpk_eq_i32 s52, 0xa8
	s_cselect_b32 s49, s3, s47
	s_cselect_b32 s48, s2, s46
	s_cselect_b32 s47, s11, s54
	s_cselect_b32 s46, s10, s53
	s_mov_b32 m0, s57
	v_lshl_add_u64 v[212:213], s[14:15], 0, v[136:137]
	ds_read_b128 v[178:181], v143
	ds_read_b128 v[182:185], v143 offset:1024
	ds_read_b128 v[186:189], v143 offset:2048
	ds_read_b128 v[190:193], v143 offset:3072
	ds_read_b128 v[194:197], v143 offset:4096
	ds_read_b128 v[198:201], v143 offset:5120
	ds_read_b128 v[202:205], v143 offset:6144
	ds_read_b128 v[208:211], v143 offset:7168
	global_load_lds_dwordx4 v[212:213], off
	v_lshl_add_u64 v[212:213], s[14:15], 0, v[138:139]
	s_mov_b32 m0, s58
	s_nop 0
	global_load_lds_dwordx4 v[212:213], off
	s_sub_u32 s98, s14, 0x2b4000
	s_subb_u32 s99, s15, 0
	v_lshl_add_u64 v[212:213], s[98:99], 0, v[136:137]
	s_mov_b32 m0, s25
	s_nop 0
	global_load_lds_dwordx4 v[212:213], off
	v_lshl_add_u64 v[212:213], s[98:99], 0, v[138:139]
	s_mov_b32 m0, s56
	s_nop 0
	global_load_lds_dwordx4 v[212:213], off
	s_waitcnt vmcnt(8)
	s_waitcnt lgkmcnt(0)
	s_barrier
	s_waitcnt lgkmcnt(0)
	v_mfma_f32_16x16x32_bf16 v[124:127], v[146:149], v[178:181], v[124:127]
	v_mfma_f32_16x16x32_bf16 v[120:123], v[154:157], v[178:181], v[120:123]
	v_mfma_f32_16x16x32_bf16 v[108:111], v[146:149], v[186:189], v[108:111]
	v_mfma_f32_16x16x32_bf16 v[104:107], v[154:157], v[186:189], v[104:107]
	v_mfma_f32_16x16x32_bf16 v[92:95], v[146:149], v[194:197], v[92:95]
	v_mfma_f32_16x16x32_bf16 v[88:91], v[154:157], v[194:197], v[88:91]
	v_mfma_f32_16x16x32_bf16 v[76:79], v[146:149], v[202:205], v[76:79]
	v_mfma_f32_16x16x32_bf16 v[72:75], v[154:157], v[202:205], v[72:75]
	v_mfma_f32_16x16x32_bf16 v[124:127], v[150:153], v[182:185], v[124:127]
	v_mfma_f32_16x16x32_bf16 v[120:123], v[158:161], v[182:185], v[120:123]
	v_mfma_f32_16x16x32_bf16 v[108:111], v[150:153], v[190:193], v[108:111]
	v_mfma_f32_16x16x32_bf16 v[104:107], v[158:161], v[190:193], v[104:107]
	v_mfma_f32_16x16x32_bf16 v[92:95], v[150:153], v[198:201], v[92:95]
	v_mfma_f32_16x16x32_bf16 v[88:91], v[158:161], v[198:201], v[88:91]
	v_mfma_f32_16x16x32_bf16 v[76:79], v[150:153], v[208:211], v[76:79]
	v_mfma_f32_16x16x32_bf16 v[72:75], v[158:161], v[208:211], v[72:75]
	v_mfma_f32_16x16x32_bf16 v[116:119], v[162:165], v[178:181], v[116:119]
	v_mfma_f32_16x16x32_bf16 v[112:115], v[170:173], v[178:181], v[112:115]
	v_mfma_f32_16x16x32_bf16 v[100:103], v[162:165], v[186:189], v[100:103]
	v_mfma_f32_16x16x32_bf16 v[96:99], v[170:173], v[186:189], v[96:99]
	v_mfma_f32_16x16x32_bf16 v[84:87], v[162:165], v[194:197], v[84:87]
	v_mfma_f32_16x16x32_bf16 v[80:83], v[170:173], v[194:197], v[80:83]
	v_mfma_f32_16x16x32_bf16 v[68:71], v[162:165], v[202:205], v[68:71]
	v_mfma_f32_16x16x32_bf16 v[64:67], v[170:173], v[202:205], v[64:67]
	v_mfma_f32_16x16x32_bf16 v[116:119], v[166:169], v[182:185], v[116:119]
	v_mfma_f32_16x16x32_bf16 v[112:115], v[174:177], v[182:185], v[112:115]
	v_mfma_f32_16x16x32_bf16 v[100:103], v[166:169], v[190:193], v[100:103]
	v_mfma_f32_16x16x32_bf16 v[96:99], v[174:177], v[190:193], v[96:99]
	v_mfma_f32_16x16x32_bf16 v[84:87], v[166:169], v[198:201], v[84:87]
	v_mfma_f32_16x16x32_bf16 v[80:83], v[174:177], v[198:201], v[80:83]
	v_mfma_f32_16x16x32_bf16 v[68:71], v[166:169], v[208:211], v[68:71]
	v_mfma_f32_16x16x32_bf16 v[64:67], v[174:177], v[208:211], v[64:67]
	s_barrier
	s_mov_b32 m0, s59
	v_lshl_add_u64 v[212:213], s[46:47], 0, v[130:131]
	s_add_u32 s54, s46, 0x2b4000
	ds_read_b128 v[178:181], v143 offset:16384
	ds_read_b128 v[182:185], v143 offset:17408
	ds_read_b128 v[186:189], v143 offset:18432
	ds_read_b128 v[190:193], v143 offset:19456
	ds_read_b128 v[194:197], v143 offset:20480
	ds_read_b128 v[198:201], v143 offset:21504
	ds_read_b128 v[202:205], v143 offset:22528
	ds_read_b128 v[208:211], v143 offset:23552
	global_load_lds_dwordx4 v[212:213], off
	v_lshl_add_u64 v[214:215], s[46:47], 0, v[134:135]
	s_mov_b32 m0, s60
	s_addc_u32 s55, s47, 0
	global_load_lds_dwordx4 v[214:215], off
	v_lshl_add_u64 v[216:217], s[54:55], 0, v[130:131]
	s_mov_b32 m0, s61
	global_load_lds_dwordx4 v[216:217], off
	v_lshl_add_u64 v[216:217], s[54:55], 0, v[134:135]
	s_mov_b32 m0, s62
	s_nop 0
	global_load_lds_dwordx4 v[216:217], off
	s_waitcnt vmcnt(4)
	s_waitcnt lgkmcnt(0)
	s_barrier
; #define PG8_STAGE(bufoff, gbase, voff) do { _Pragma("unroll") for (int _i = 0; _i < 2; ++_i) \
;         __builtin_amdgcn_global_load_lds((const unsigned*)((const char*)(gbase) + (voff)[_i]), (PG8_LAS unsigned*)(lds + (bufoff) + ldsw + _i * 8192), 16, 0, 0); } while (0)
; #define PG8_LDA(dst, b, h) do { _Pragma("unroll") for (int m = 0; m < 4; ++m) _Pragma("unroll") for (int k = 0; k < 2; ++k) dst[m][k] = *(const PG8_LAS bf16x8*)(lds + PG8_SA(b, h) + aoff + m * 2048 + k * 1024); } while (0)
; #define PG8_LDB(dst, b, h) do { _Pragma("unroll") for (int n = 0; n < 2; ++n) _Pragma("unroll") for (int k = 0; k < 2; ++k) dst[n][k] = *(const PG8_LAS bf16x8*)(lds + PG8_SB(b, h) + boff + n * 2048 + k * 1024); } while (0)
; #define PG8_MMA(ai, bj, At, Bt) do { __builtin_amdgcn_s_setprio(1); _Pragma("unroll") for (int m = 0; m < 4; ++m) _Pragma("unroll") for (int n = 0; n < 2; ++n) _Pragma("unroll") for (int k = 0; k < 2; ++k) \
;         acc[ai][bj][m][n] = __builtin_amdgcn_mfma_f32_16x16x32_bf16(Bt[n][k], At[m][k], acc[ai][bj][m][n], 0, 0, 0); __builtin_amdgcn_s_setprio(0); } while (0)
; #define PG8_WAIT_V(n) asm volatile("s_waitcnt vmcnt(" #n ")" ::: "memory")
; #define PG8_WAIT_L(n) asm volatile("s_waitcnt lgkmcnt(" #n ")" ::: "memory")
; #define PG8_BAR __builtin_amdgcn_s_barrier()
; #define PG8_SCHED __builtin_amdgcn_sched_barrier(0)
; template <class Epi, class Sched, bool ALIGN_EPI = false, bool SP2 = false>
; __device__ __forceinline__ void gemm_phase(PG8_LAS unsigned char* lds, const Gemm g, const Sched& S, const Epi& E, int wid) {
;     ...
;             PG8_WAIT_V(8); PG8_WAIT_L(0); PG8_BAR; PG8_MMA(1, 0, At, B0); PG8_MMA(1, 1, At, B1); PG8_BAR; PG8_SCHED;
;             PG8_LDB(B0, 1, 0); PG8_LDB(B1, 1, 1); PG8_SCHED; PG8_LDA(At, 1, 0); PG8_STAGE(PG8_SA(0, 1), a2 + hstepA, voffA);
;             PG8_WAIT_V(8); PG8_WAIT_L(0); PG8_BAR; PG8_MMA(0, 0, At, B0); PG8_MMA(0, 1, At, B1); PG8_BAR; PG8_SCHED;
	s_waitcnt lgkmcnt(0)
	v_mfma_f32_16x16x32_bf16 v[60:63], v[146:149], v[178:181], v[60:63]
	v_mfma_f32_16x16x32_bf16 v[56:59], v[154:157], v[178:181], v[56:59]
	v_mfma_f32_16x16x32_bf16 v[44:47], v[146:149], v[186:189], v[44:47]
	v_mfma_f32_16x16x32_bf16 v[40:43], v[154:157], v[186:189], v[40:43]
	v_mfma_f32_16x16x32_bf16 v[28:31], v[146:149], v[194:197], v[28:31]
	v_mfma_f32_16x16x32_bf16 v[24:27], v[154:157], v[194:197], v[24:27]
	v_mfma_f32_16x16x32_bf16 v[12:15], v[146:149], v[202:205], v[12:15]
	v_mfma_f32_16x16x32_bf16 v[8:11], v[154:157], v[202:205], v[8:11]
	v_mfma_f32_16x16x32_bf16 v[60:63], v[150:153], v[182:185], v[60:63]
	v_mfma_f32_16x16x32_bf16 v[56:59], v[158:161], v[182:185], v[56:59]
	v_mfma_f32_16x16x32_bf16 v[44:47], v[150:153], v[190:193], v[44:47]
	v_mfma_f32_16x16x32_bf16 v[40:43], v[158:161], v[190:193], v[40:43]
	v_mfma_f32_16x16x32_bf16 v[28:31], v[150:153], v[198:201], v[28:31]
	v_mfma_f32_16x16x32_bf16 v[24:27], v[158:161], v[198:201], v[24:27]
	v_mfma_f32_16x16x32_bf16 v[12:15], v[150:153], v[208:211], v[12:15]
	v_mfma_f32_16x16x32_bf16 v[8:11], v[158:161], v[208:211], v[8:11]
	v_mfma_f32_16x16x32_bf16 v[52:55], v[162:165], v[178:181], v[52:55]
	v_mfma_f32_16x16x32_bf16 v[48:51], v[170:173], v[178:181], v[48:51]
	v_mfma_f32_16x16x32_bf16 v[36:39], v[162:165], v[186:189], v[36:39]
	v_mfma_f32_16x16x32_bf16 v[32:35], v[170:173], v[186:189], v[32:35]
	v_mfma_f32_16x16x32_bf16 v[20:23], v[162:165], v[194:197], v[20:23]
	v_mfma_f32_16x16x32_bf16 v[16:19], v[170:173], v[194:197], v[16:19]
	v_mfma_f32_16x16x32_bf16 v[4:7], v[162:165], v[202:205], v[4:7]
	v_mfma_f32_16x16x32_bf16 v[0:3], v[170:173], v[202:205], v[0:3]
	v_mfma_f32_16x16x32_bf16 v[52:55], v[166:169], v[182:185], v[52:55]
	v_mfma_f32_16x16x32_bf16 v[48:51], v[174:177], v[182:185], v[48:51]
	v_mfma_f32_16x16x32_bf16 v[36:39], v[166:169], v[190:193], v[36:39]
	v_mfma_f32_16x16x32_bf16 v[32:35], v[174:177], v[190:193], v[32:35]
	v_mfma_f32_16x16x32_bf16 v[20:23], v[166:169], v[198:201], v[20:23]
	v_mfma_f32_16x16x32_bf16 v[16:19], v[174:177], v[198:201], v[16:19]
	v_mfma_f32_16x16x32_bf16 v[4:7], v[166:169], v[208:211], v[4:7]
	v_mfma_f32_16x16x32_bf16 v[0:3], v[174:177], v[208:211], v[0:3]
	s_barrier
	ds_read_b128 v[146:149], v144
	ds_read_b128 v[150:153], v144 offset:1024
	ds_read_b128 v[154:157], v144 offset:2048
	ds_read_b128 v[158:161], v144 offset:3072
	ds_read_b128 v[162:165], v145
	ds_read_b128 v[166:169], v145 offset:1024
	ds_read_b128 v[170:173], v145 offset:2048
	ds_read_b128 v[174:177], v145 offset:3072
	v_lshl_add_u64 v[220:221], s[48:49], 0, v[128:129]
	s_mov_b32 m0, s17
	s_nop 0
	global_load_lds_dwordx4 v[220:221], off
	v_lshl_add_u64 v[220:221], s[48:49], 0, v[132:133]
	s_mov_b32 m0, s19
	s_nop 0
	global_load_lds_dwordx4 v[220:221], off
	s_add_u32 s48, s48, 0x2b4000
	s_addc_u32 s49, s49, 0
	s_mov_b32 m0, s22
	v_lshl_add_u64 v[220:221], s[48:49], 0, v[128:129]
	ds_read_b128 v[178:181], v143 offset:32768
	ds_read_b128 v[182:185], v143 offset:33792
	ds_read_b128 v[186:189], v143 offset:34816
	ds_read_b128 v[190:193], v143 offset:35840
	ds_read_b128 v[194:197], v143 offset:36864
	ds_read_b128 v[198:201], v143 offset:37888
	ds_read_b128 v[202:205], v143 offset:38912
	ds_read_b128 v[208:211], v143 offset:39936
	global_load_lds_dwordx4 v[220:221], off
	v_lshl_add_u64 v[220:221], s[48:49], 0, v[132:133]
	s_mov_b32 m0, s23
	s_nop 0
	global_load_lds_dwordx4 v[220:221], off
	s_waitcnt vmcnt(8)
	s_waitcnt lgkmcnt(0)
	s_barrier
	s_waitcnt lgkmcnt(0)
	v_mfma_f32_16x16x32_bf16 v[124:127], v[146:149], v[178:181], v[124:127]
	v_mfma_f32_16x16x32_bf16 v[120:123], v[154:157], v[178:181], v[120:123]
	v_mfma_f32_16x16x32_bf16 v[108:111], v[146:149], v[186:189], v[108:111]
	v_mfma_f32_16x16x32_bf16 v[104:107], v[154:157], v[186:189], v[104:107]
	v_mfma_f32_16x16x32_bf16 v[92:95], v[146:149], v[194:197], v[92:95]
	v_mfma_f32_16x16x32_bf16 v[88:91], v[154:157], v[194:197], v[88:91]
	v_mfma_f32_16x16x32_bf16 v[76:79], v[146:149], v[202:205], v[76:79]
	v_mfma_f32_16x16x32_bf16 v[72:75], v[154:157], v[202:205], v[72:75]
	v_mfma_f32_16x16x32_bf16 v[124:127], v[150:153], v[182:185], v[124:127]
	v_mfma_f32_16x16x32_bf16 v[120:123], v[158:161], v[182:185], v[120:123]
	v_mfma_f32_16x16x32_bf16 v[108:111], v[150:153], v[190:193], v[108:111]
	v_mfma_f32_16x16x32_bf16 v[104:107], v[158:161], v[190:193], v[104:107]
	v_mfma_f32_16x16x32_bf16 v[92:95], v[150:153], v[198:201], v[92:95]
	v_mfma_f32_16x16x32_bf16 v[88:91], v[158:161], v[198:201], v[88:91]
	v_mfma_f32_16x16x32_bf16 v[76:79], v[150:153], v[208:211], v[76:79]
	v_mfma_f32_16x16x32_bf16 v[72:75], v[158:161], v[208:211], v[72:75]
	v_mfma_f32_16x16x32_bf16 v[116:119], v[162:165], v[178:181], v[116:119]
	v_mfma_f32_16x16x32_bf16 v[112:115], v[170:173], v[178:181], v[112:115]
	v_mfma_f32_16x16x32_bf16 v[100:103], v[162:165], v[186:189], v[100:103]
	v_mfma_f32_16x16x32_bf16 v[96:99], v[170:173], v[186:189], v[96:99]
	v_mfma_f32_16x16x32_bf16 v[84:87], v[162:165], v[194:197], v[84:87]
	v_mfma_f32_16x16x32_bf16 v[80:83], v[170:173], v[194:197], v[80:83]
	v_mfma_f32_16x16x32_bf16 v[68:71], v[162:165], v[202:205], v[68:71]
	v_mfma_f32_16x16x32_bf16 v[64:67], v[170:173], v[202:205], v[64:67]
	v_mfma_f32_16x16x32_bf16 v[116:119], v[166:169], v[182:185], v[116:119]
	v_mfma_f32_16x16x32_bf16 v[112:115], v[174:177], v[182:185], v[112:115]
	v_mfma_f32_16x16x32_bf16 v[100:103], v[166:169], v[190:193], v[100:103]
	v_mfma_f32_16x16x32_bf16 v[96:99], v[174:177], v[190:193], v[96:99]
	v_mfma_f32_16x16x32_bf16 v[84:87], v[166:169], v[198:201], v[84:87]
	v_mfma_f32_16x16x32_bf16 v[80:83], v[174:177], v[198:201], v[80:83]
	v_mfma_f32_16x16x32_bf16 v[68:71], v[166:169], v[208:211], v[68:71]
	v_mfma_f32_16x16x32_bf16 v[64:67], v[174:177], v[208:211], v[64:67]
	s_barrier
; #define PG8_STAGE(bufoff, gbase, voff) do { _Pragma("unroll") for (int _i = 0; _i < 2; ++_i) \
;         __builtin_amdgcn_global_load_lds((const unsigned*)((const char*)(gbase) + (voff)[_i]), (PG8_LAS unsigned*)(lds + (bufoff) + ldsw + _i * 8192), 16, 0, 0); } while (0)
; #define PG8_STAGE_NT(bufoff, gbase, voff) do { _Pragma("unroll") for (int _i = 0; _i < 2; ++_i) \
;         __builtin_amdgcn_global_load_lds((const unsigned*)((const char*)(gbase) + (voff)[_i]), (PG8_LAS unsigned*)(lds + (bufoff) + ldsw + _i * 8192), 16, 0, PG8_B_AUX); } while (0)
; #define PG8_LDA(dst, b, h) do { _Pragma("unroll") for (int m = 0; m < 4; ++m) _Pragma("unroll") for (int k = 0; k < 2; ++k) dst[m][k] = *(const PG8_LAS bf16x8*)(lds + PG8_SA(b, h) + aoff + m * 2048 + k * 1024); } while (0)
; #define PG8_MMA(ai, bj, At, Bt) do { __builtin_amdgcn_s_setprio(1); _Pragma("unroll") for (int m = 0; m < 4; ++m) _Pragma("unroll") for (int n = 0; n < 2; ++n) _Pragma("unroll") for (int k = 0; k < 2; ++k) \
;         acc[ai][bj][m][n] = __builtin_amdgcn_mfma_f32_16x16x32_bf16(Bt[n][k], At[m][k], acc[ai][bj][m][n], 0, 0, 0); __builtin_amdgcn_s_setprio(0); } while (0)
; #define PG8_WAIT_V(n) asm volatile("s_waitcnt vmcnt(" #n ")" ::: "memory")
; #define PG8_WAIT_L(n) asm volatile("s_waitcnt lgkmcnt(" #n ")" ::: "memory")
; #define PG8_BAR __builtin_amdgcn_s_barrier()
; #define PG8_SCHED __builtin_amdgcn_sched_barrier(0)
; template <class Epi, class Sched, bool ALIGN_EPI = false, bool SP2 = false>
; __device__ __forceinline__ void gemm_phase(PG8_LAS unsigned char* lds, const Gemm g, const Sched& S, const Epi& E, int wid) {
;     ...
;             PG8_LDA(At, 1, 1); PG8_STAGE_NT(PG8_SB(1, 0), b3, voffB); PG8_STAGE_NT(PG8_SB(1, 1), b3 + hstepB, voffB); PG8_STAGE(PG8_SA(1, 0), a3, voffA);
;             PG8_WAIT_V(8); PG8_WAIT_L(0); PG8_BAR; PG8_MMA(1, 0, At, B0); PG8_MMA(1, 1, At, B1); PG8_BAR; PG8_SCHED;
;     ...
;     PG8_WAIT_V(0);
;     if constexpr (!ALIGN_EPI) { if (wr == 0) PG8_BAR; }
	s_mov_b32 m0, s63
	v_lshl_add_u64 v[212:213], v[212:213], 0, s[4:5]
	s_add_u32 s46, s46, 0x2b4080
	ds_read_b128 v[178:181], v143 offset:49152
	ds_read_b128 v[182:185], v143 offset:50176
	ds_read_b128 v[186:189], v143 offset:51200
	ds_read_b128 v[190:193], v143 offset:52224
	ds_read_b128 v[194:197], v143 offset:53248
	ds_read_b128 v[198:201], v143 offset:54272
	ds_read_b128 v[202:205], v143 offset:55296
	ds_read_b128 v[208:211], v143 offset:56320
	global_load_lds_dwordx4 v[212:213], off
	v_lshl_add_u64 v[212:213], v[214:215], 0, s[4:5]
	s_mov_b32 m0, s64
	s_addc_u32 s47, s47, 0
	global_load_lds_dwordx4 v[212:213], off
	v_lshl_add_u64 v[212:213], s[46:47], 0, v[130:131]
	s_mov_b32 m0, s65
	s_nop 0
	global_load_lds_dwordx4 v[212:213], off
	v_lshl_add_u64 v[212:213], s[46:47], 0, v[134:135]
	s_mov_b32 m0, s66
	s_nop 0
	global_load_lds_dwordx4 v[212:213], off
	s_waitcnt vmcnt(4)
	s_waitcnt lgkmcnt(0)
	s_barrier
	s_waitcnt lgkmcnt(0)
	v_mfma_f32_16x16x32_bf16 v[60:63], v[146:149], v[178:181], v[60:63]
	v_mfma_f32_16x16x32_bf16 v[56:59], v[154:157], v[178:181], v[56:59]
	v_mfma_f32_16x16x32_bf16 v[44:47], v[146:149], v[186:189], v[44:47]
	v_mfma_f32_16x16x32_bf16 v[40:43], v[154:157], v[186:189], v[40:43]
	v_mfma_f32_16x16x32_bf16 v[28:31], v[146:149], v[194:197], v[28:31]
	v_mfma_f32_16x16x32_bf16 v[24:27], v[154:157], v[194:197], v[24:27]
	v_mfma_f32_16x16x32_bf16 v[12:15], v[146:149], v[202:205], v[12:15]
	v_mfma_f32_16x16x32_bf16 v[8:11], v[154:157], v[202:205], v[8:11]
	v_mfma_f32_16x16x32_bf16 v[60:63], v[150:153], v[182:185], v[60:63]
	v_mfma_f32_16x16x32_bf16 v[56:59], v[158:161], v[182:185], v[56:59]
	v_mfma_f32_16x16x32_bf16 v[44:47], v[150:153], v[190:193], v[44:47]
	v_mfma_f32_16x16x32_bf16 v[40:43], v[158:161], v[190:193], v[40:43]
	v_mfma_f32_16x16x32_bf16 v[28:31], v[150:153], v[198:201], v[28:31]
	v_mfma_f32_16x16x32_bf16 v[24:27], v[158:161], v[198:201], v[24:27]
	v_mfma_f32_16x16x32_bf16 v[12:15], v[150:153], v[208:211], v[12:15]
	v_mfma_f32_16x16x32_bf16 v[8:11], v[158:161], v[208:211], v[8:11]
	v_mfma_f32_16x16x32_bf16 v[52:55], v[162:165], v[178:181], v[52:55]
	v_mfma_f32_16x16x32_bf16 v[48:51], v[170:173], v[178:181], v[48:51]
	v_mfma_f32_16x16x32_bf16 v[36:39], v[162:165], v[186:189], v[36:39]
	v_mfma_f32_16x16x32_bf16 v[32:35], v[170:173], v[186:189], v[32:35]
	v_mfma_f32_16x16x32_bf16 v[20:23], v[162:165], v[194:197], v[20:23]
	v_mfma_f32_16x16x32_bf16 v[16:19], v[170:173], v[194:197], v[16:19]
	v_mfma_f32_16x16x32_bf16 v[4:7], v[162:165], v[202:205], v[4:7]
	v_mfma_f32_16x16x32_bf16 v[0:3], v[170:173], v[202:205], v[0:3]
	v_mfma_f32_16x16x32_bf16 v[52:55], v[166:169], v[182:185], v[52:55]
	v_mfma_f32_16x16x32_bf16 v[48:51], v[174:177], v[182:185], v[48:51]
	v_mfma_f32_16x16x32_bf16 v[36:39], v[166:169], v[190:193], v[36:39]
	v_mfma_f32_16x16x32_bf16 v[32:35], v[174:177], v[190:193], v[32:35]
	v_mfma_f32_16x16x32_bf16 v[20:23], v[166:169], v[198:201], v[20:23]
	v_mfma_f32_16x16x32_bf16 v[16:19], v[174:177], v[198:201], v[16:19]
	v_mfma_f32_16x16x32_bf16 v[4:7], v[166:169], v[208:211], v[4:7]
	v_mfma_f32_16x16x32_bf16 v[0:3], v[174:177], v[208:211], v[0:3]
	s_barrier
	s_add_i32 s52, s52, 2
	s_add_u32 s50, s50, 0x100
	s_addc_u32 s51, s51, 0
	s_add_u32 s44, s44, 0x100
	s_addc_u32 s45, s45, 0
	v_lshl_add_u64 v[136:137], v[136:137], 0, s[42:43]
	s_cmpk_lt_u32 s52, 0xaa
	v_lshl_add_u64 v[138:139], v[138:139], 0, s[42:43]
	s_cbranch_scc1 .LBB0_1249
	s_waitcnt vmcnt(0)
	s_cmpk_lt_u32 s95, 0x100
	s_cselect_b64 s[44:45], -1, 0
	s_cmpk_gt_u32 s95, 0xff
	s_cbranch_scc1 .LBB0_1252
	s_barrier

; #define PG8_STAGE(bufoff, gbase, voff) do { _Pragma("unroll") for (int _i = 0; _i < 2; ++_i) \
;         __builtin_amdgcn_global_load_lds((const unsigned*)((const char*)(gbase) + (voff)[_i]), (PG8_LAS unsigned*)(lds + (bufoff) + ldsw + _i * 8192), 16, 0, 0); } while (0)
; #define PG8_STAGE_NT(bufoff, gbase, voff) do { _Pragma("unroll") for (int _i = 0; _i < 2; ++_i) \
;         __builtin_amdgcn_global_load_lds((const unsigned*)((const char*)(gbase) + (voff)[_i]), (PG8_LAS unsigned*)(lds + (bufoff) + ldsw + _i * 8192), 16, 0, PG8_B_AUX); } while (0)
; #define PG8_LDA(dst, b, h) do { _Pragma("unroll") for (int m = 0; m < 4; ++m) _Pragma("unroll") for (int k = 0; k < 2; ++k) dst[m][k] = *(const PG8_LAS bf16x8*)(lds + PG8_SA(b, h) + aoff + m * 2048 + k * 1024); } while (0)
; #define PG8_LDB(dst, b, h) do { _Pragma("unroll") for (int n = 0; n < 2; ++n) _Pragma("unroll") for (int k = 0; k < 2; ++k) dst[n][k] = *(const PG8_LAS bf16x8*)(lds + PG8_SB(b, h) + boff + n * 2048 + k * 1024); } while (0)
; #define PG8_WAIT_V(n) asm volatile("s_waitcnt vmcnt(" #n ")" ::: "memory")
; #define PG8_WAIT_L(n) asm volatile("s_waitcnt lgkmcnt(" #n ")" ::: "memory")
; #define PG8_BAR __builtin_amdgcn_s_barrier()
; template <class Epi, class Sched, bool ALIGN_EPI = false, bool SP2 = false>
; __device__ __forceinline__ void gemm_phase(PG8_LAS unsigned char* lds, const Gemm g, const Sched& S, const Epi& E, int wid) {
;     ...
;         for (int t = 0; t < nt; t += 2) {
;             const bool last = (t == nt - 2);
;             const char* a1 = cA + (size_t)(t + 1) * kstep;
;             const char* a2 = last ? nA : cA + (size_t)(t + 2) * kstep; const char* b2 = last ? nB : cB + (size_t)(t + 2) * kstep;
;             const char* a3 = a2 + kstep; const char* b3 = b2 + kstep;
;             if (last && has_next) S.a_ready(nxt);
;             if constexpr (SP2) {
;             PG8_LDB(B0, 0, 0); PG8_LDB(B1, 0, 1); PG8_SCHED; PG8_LDA(At, 0, 0); PG8_STAGE(PG8_SA(1, 1), a1 + hstepA, voffA);
;             PG8_WAIT_V(8); PG8_WAIT_L(0); PG8_BAR; PG8_MMA(0, 0, At, B0); PG8_MMA(0, 1, At, B1); PG8_BAR; PG8_SCHED;
;             PG8_LDA(At, 0, 1); PG8_STAGE_NT(PG8_SB(0, 0), b2, voffB); PG8_STAGE_NT(PG8_SB(0, 1), b2 + hstepB, voffB); PG8_STAGE(PG8_SA(0, 0), a2, voffA);
;             PG8_WAIT_V(8); PG8_WAIT_L(0); PG8_BAR; PG8_MMA(1, 0, At, B0); PG8_MMA(1, 1, At, B1); PG8_BAR; PG8_SCHED;
.LBB0_1307:
	ds_read_b128 v[146:149], v141
	ds_read_b128 v[150:153], v141 offset:1024
	ds_read_b128 v[154:157], v141 offset:2048
	ds_read_b128 v[158:161], v141 offset:3072
	ds_read_b128 v[162:165], v142
	ds_read_b128 v[166:169], v142 offset:1024
	ds_read_b128 v[170:173], v142 offset:2048
	ds_read_b128 v[174:177], v142 offset:3072
	s_add_u32 s30, s14, s21
	s_addc_u32 s31, s15, s40
	s_add_u32 s48, s14, s8
	s_addc_u32 s49, s15, s9
	s_cmpk_eq_i32 s41, 0xa8
	s_cselect_b32 s39, s3, s31
	s_cselect_b32 s38, s2, s30
	s_cselect_b32 s31, s11, s49
	s_cselect_b32 s30, s10, s48
	s_mov_b32 m0, s57
	v_lshl_add_u64 v[202:203], s[14:15], 0, v[136:137]
	ds_read_b128 v[178:181], v143
	ds_read_b128 v[182:185], v143 offset:1024
	ds_read_b128 v[186:189], v143 offset:2048
	ds_read_b128 v[190:193], v143 offset:3072
	ds_read_b128 v[194:197], v143 offset:4096
	ds_read_b128 v[198:201], v143 offset:5120
	ds_read_b128 v[208:211], v143 offset:6144
	ds_read_b128 v[212:215], v143 offset:7168
	global_load_lds_dwordx4 v[202:203], off
	v_lshl_add_u64 v[202:203], s[14:15], 0, v[138:139]
	s_mov_b32 m0, s58
	s_nop 0
	global_load_lds_dwordx4 v[202:203], off
	s_sub_u32 s98, s14, 0x2b4000
	s_subb_u32 s99, s15, 0
	v_lshl_add_u64 v[202:203], s[98:99], 0, v[136:137]
	s_mov_b32 m0, s25
	s_nop 0
	global_load_lds_dwordx4 v[202:203], off
	v_lshl_add_u64 v[202:203], s[98:99], 0, v[138:139]
	s_mov_b32 m0, s56
	s_nop 0
	global_load_lds_dwordx4 v[202:203], off
	s_waitcnt vmcnt(8)
	s_waitcnt lgkmcnt(0)
	s_barrier
	s_waitcnt lgkmcnt(0)
	v_mfma_f32_16x16x32_bf16 v[124:127], v[146:149], v[178:181], v[124:127]
	v_mfma_f32_16x16x32_bf16 v[120:123], v[154:157], v[178:181], v[120:123]
	v_mfma_f32_16x16x32_bf16 v[108:111], v[146:149], v[186:189], v[108:111]
	v_mfma_f32_16x16x32_bf16 v[104:107], v[154:157], v[186:189], v[104:107]
	v_mfma_f32_16x16x32_bf16 v[92:95], v[146:149], v[194:197], v[92:95]
	v_mfma_f32_16x16x32_bf16 v[88:91], v[154:157], v[194:197], v[88:91]
	v_mfma_f32_16x16x32_bf16 v[76:79], v[146:149], v[208:211], v[76:79]
	v_mfma_f32_16x16x32_bf16 v[72:75], v[154:157], v[208:211], v[72:75]
	v_mfma_f32_16x16x32_bf16 v[124:127], v[150:153], v[182:185], v[124:127]
	v_mfma_f32_16x16x32_bf16 v[120:123], v[158:161], v[182:185], v[120:123]
	v_mfma_f32_16x16x32_bf16 v[108:111], v[150:153], v[190:193], v[108:111]
	v_mfma_f32_16x16x32_bf16 v[104:107], v[158:161], v[190:193], v[104:107]
	v_mfma_f32_16x16x32_bf16 v[92:95], v[150:153], v[198:201], v[92:95]
	v_mfma_f32_16x16x32_bf16 v[88:91], v[158:161], v[198:201], v[88:91]
	v_mfma_f32_16x16x32_bf16 v[76:79], v[150:153], v[212:215], v[76:79]
	v_mfma_f32_16x16x32_bf16 v[72:75], v[158:161], v[212:215], v[72:75]
	v_mfma_f32_16x16x32_bf16 v[116:119], v[162:165], v[178:181], v[116:119]
	v_mfma_f32_16x16x32_bf16 v[112:115], v[170:173], v[178:181], v[112:115]
	v_mfma_f32_16x16x32_bf16 v[100:103], v[162:165], v[186:189], v[100:103]
	v_mfma_f32_16x16x32_bf16 v[96:99], v[170:173], v[186:189], v[96:99]
	v_mfma_f32_16x16x32_bf16 v[84:87], v[162:165], v[194:197], v[84:87]
	v_mfma_f32_16x16x32_bf16 v[80:83], v[170:173], v[194:197], v[80:83]
	v_mfma_f32_16x16x32_bf16 v[68:71], v[162:165], v[208:211], v[68:71]
	v_mfma_f32_16x16x32_bf16 v[64:67], v[170:173], v[208:211], v[64:67]
	v_mfma_f32_16x16x32_bf16 v[116:119], v[166:169], v[182:185], v[116:119]
	v_mfma_f32_16x16x32_bf16 v[112:115], v[174:177], v[182:185], v[112:115]
	v_mfma_f32_16x16x32_bf16 v[100:103], v[166:169], v[190:193], v[100:103]
	v_mfma_f32_16x16x32_bf16 v[96:99], v[174:177], v[190:193], v[96:99]
	v_mfma_f32_16x16x32_bf16 v[84:87], v[166:169], v[198:201], v[84:87]
	v_mfma_f32_16x16x32_bf16 v[80:83], v[174:177], v[198:201], v[80:83]
	v_mfma_f32_16x16x32_bf16 v[68:71], v[166:169], v[212:215], v[68:71]
	v_mfma_f32_16x16x32_bf16 v[64:67], v[174:177], v[212:215], v[64:67]
	s_barrier
	s_mov_b32 m0, s59
	v_lshl_add_u64 v[202:203], s[30:31], 0, v[130:131]
	s_add_u32 s48, s30, 0x2b4000
	ds_read_b128 v[178:181], v143 offset:16384
	ds_read_b128 v[182:185], v143 offset:17408
	ds_read_b128 v[186:189], v143 offset:18432
	ds_read_b128 v[190:193], v143 offset:19456
	ds_read_b128 v[194:197], v143 offset:20480
	ds_read_b128 v[198:201], v143 offset:21504
	ds_read_b128 v[208:211], v143 offset:22528
	ds_read_b128 v[212:215], v143 offset:23552
	global_load_lds_dwordx4 v[202:203], off
	v_lshl_add_u64 v[216:217], s[30:31], 0, v[134:135]
	s_mov_b32 m0, s60
	s_addc_u32 s49, s31, 0
	global_load_lds_dwordx4 v[216:217], off
	v_lshl_add_u64 v[218:219], s[48:49], 0, v[130:131]
	s_mov_b32 m0, s61
	global_load_lds_dwordx4 v[218:219], off
	v_lshl_add_u64 v[218:219], s[48:49], 0, v[134:135]
	s_mov_b32 m0, s62
	s_nop 0
	global_load_lds_dwordx4 v[218:219], off
	s_waitcnt vmcnt(4)
	s_waitcnt lgkmcnt(0)
	s_barrier
; #define PG8_STAGE(bufoff, gbase, voff) do { _Pragma("unroll") for (int _i = 0; _i < 2; ++_i) \
;         __builtin_amdgcn_global_load_lds((const unsigned*)((const char*)(gbase) + (voff)[_i]), (PG8_LAS unsigned*)(lds + (bufoff) + ldsw + _i * 8192), 16, 0, 0); } while (0)
; #define PG8_LDA(dst, b, h) do { _Pragma("unroll") for (int m = 0; m < 4; ++m) _Pragma("unroll") for (int k = 0; k < 2; ++k) dst[m][k] = *(const PG8_LAS bf16x8*)(lds + PG8_SA(b, h) + aoff + m * 2048 + k * 1024); } while (0)
; #define PG8_LDB(dst, b, h) do { _Pragma("unroll") for (int n = 0; n < 2; ++n) _Pragma("unroll") for (int k = 0; k < 2; ++k) dst[n][k] = *(const PG8_LAS bf16x8*)(lds + PG8_SB(b, h) + boff + n * 2048 + k * 1024); } while (0)
; #define PG8_MMA(ai, bj, At, Bt) do { __builtin_amdgcn_s_setprio(1); _Pragma("unroll") for (int m = 0; m < 4; ++m) _Pragma("unroll") for (int n = 0; n < 2; ++n) _Pragma("unroll") for (int k = 0; k < 2; ++k) \
;         acc[ai][bj][m][n] = __builtin_amdgcn_mfma_f32_16x16x32_bf16(Bt[n][k], At[m][k], acc[ai][bj][m][n], 0, 0, 0); __builtin_amdgcn_s_setprio(0); } while (0)
; #define PG8_WAIT_V(n) asm volatile("s_waitcnt vmcnt(" #n ")" ::: "memory")
; #define PG8_WAIT_L(n) asm volatile("s_waitcnt lgkmcnt(" #n ")" ::: "memory")
; #define PG8_BAR __builtin_amdgcn_s_barrier()
; #define PG8_SCHED __builtin_amdgcn_sched_barrier(0)
; template <class Epi, class Sched, bool ALIGN_EPI = false, bool SP2 = false>
; __device__ __forceinline__ void gemm_phase(PG8_LAS unsigned char* lds, const Gemm g, const Sched& S, const Epi& E, int wid) {
;     ...
;             PG8_WAIT_V(8); PG8_WAIT_L(0); PG8_BAR; PG8_MMA(1, 0, At, B0); PG8_MMA(1, 1, At, B1); PG8_BAR; PG8_SCHED;
;             PG8_LDB(B0, 1, 0); PG8_LDB(B1, 1, 1); PG8_SCHED; PG8_LDA(At, 1, 0); PG8_STAGE(PG8_SA(0, 1), a2 + hstepA, voffA);
;             PG8_WAIT_V(8); PG8_WAIT_L(0); PG8_BAR; PG8_MMA(0, 0, At, B0); PG8_MMA(0, 1, At, B1); PG8_BAR; PG8_SCHED;
	s_waitcnt lgkmcnt(0)
	v_mfma_f32_16x16x32_bf16 v[60:63], v[146:149], v[178:181], v[60:63]
	v_mfma_f32_16x16x32_bf16 v[56:59], v[154:157], v[178:181], v[56:59]
	v_mfma_f32_16x16x32_bf16 v[44:47], v[146:149], v[186:189], v[44:47]
	v_mfma_f32_16x16x32_bf16 v[40:43], v[154:157], v[186:189], v[40:43]
	v_mfma_f32_16x16x32_bf16 v[28:31], v[146:149], v[194:197], v[28:31]
	v_mfma_f32_16x16x32_bf16 v[24:27], v[154:157], v[194:197], v[24:27]
	v_mfma_f32_16x16x32_bf16 v[12:15], v[146:149], v[208:211], v[12:15]
	v_mfma_f32_16x16x32_bf16 v[8:11], v[154:157], v[208:211], v[8:11]
	v_mfma_f32_16x16x32_bf16 v[60:63], v[150:153], v[182:185], v[60:63]
	v_mfma_f32_16x16x32_bf16 v[56:59], v[158:161], v[182:185], v[56:59]
	v_mfma_f32_16x16x32_bf16 v[44:47], v[150:153], v[190:193], v[44:47]
	v_mfma_f32_16x16x32_bf16 v[40:43], v[158:161], v[190:193], v[40:43]
	v_mfma_f32_16x16x32_bf16 v[28:31], v[150:153], v[198:201], v[28:31]
	v_mfma_f32_16x16x32_bf16 v[24:27], v[158:161], v[198:201], v[24:27]
	v_mfma_f32_16x16x32_bf16 v[12:15], v[150:153], v[212:215], v[12:15]
	v_mfma_f32_16x16x32_bf16 v[8:11], v[158:161], v[212:215], v[8:11]
	v_mfma_f32_16x16x32_bf16 v[52:55], v[162:165], v[178:181], v[52:55]
	v_mfma_f32_16x16x32_bf16 v[48:51], v[170:173], v[178:181], v[48:51]
	v_mfma_f32_16x16x32_bf16 v[36:39], v[162:165], v[186:189], v[36:39]
	v_mfma_f32_16x16x32_bf16 v[32:35], v[170:173], v[186:189], v[32:35]
	v_mfma_f32_16x16x32_bf16 v[20:23], v[162:165], v[194:197], v[20:23]
	v_mfma_f32_16x16x32_bf16 v[16:19], v[170:173], v[194:197], v[16:19]
	v_mfma_f32_16x16x32_bf16 v[4:7], v[162:165], v[208:211], v[4:7]
	v_mfma_f32_16x16x32_bf16 v[0:3], v[170:173], v[208:211], v[0:3]
	v_mfma_f32_16x16x32_bf16 v[52:55], v[166:169], v[182:185], v[52:55]
	v_mfma_f32_16x16x32_bf16 v[48:51], v[174:177], v[182:185], v[48:51]
	v_mfma_f32_16x16x32_bf16 v[36:39], v[166:169], v[190:193], v[36:39]
	v_mfma_f32_16x16x32_bf16 v[32:35], v[174:177], v[190:193], v[32:35]
	v_mfma_f32_16x16x32_bf16 v[20:23], v[166:169], v[198:201], v[20:23]
	v_mfma_f32_16x16x32_bf16 v[16:19], v[174:177], v[198:201], v[16:19]
	v_mfma_f32_16x16x32_bf16 v[4:7], v[166:169], v[212:215], v[4:7]
	v_mfma_f32_16x16x32_bf16 v[0:3], v[174:177], v[212:215], v[0:3]
	s_barrier
	ds_read_b128 v[146:149], v144
	ds_read_b128 v[150:153], v144 offset:1024
	ds_read_b128 v[154:157], v144 offset:2048
	ds_read_b128 v[158:161], v144 offset:3072
	ds_read_b128 v[162:165], v145
	ds_read_b128 v[166:169], v145 offset:1024
	ds_read_b128 v[170:173], v145 offset:2048
	ds_read_b128 v[174:177], v145 offset:3072
	v_lshl_add_u64 v[222:223], s[38:39], 0, v[128:129]
	s_mov_b32 m0, s17
	s_nop 0
	global_load_lds_dwordx4 v[222:223], off
	v_lshl_add_u64 v[222:223], s[38:39], 0, v[132:133]
	s_mov_b32 m0, s19
	s_nop 0
	global_load_lds_dwordx4 v[222:223], off
	s_add_u32 s38, s38, 0x2b4000
	s_addc_u32 s39, s39, 0
	s_mov_b32 m0, s22
	v_lshl_add_u64 v[222:223], s[38:39], 0, v[128:129]
	ds_read_b128 v[178:181], v143 offset:32768
	ds_read_b128 v[182:185], v143 offset:33792
	ds_read_b128 v[186:189], v143 offset:34816
	ds_read_b128 v[190:193], v143 offset:35840
	ds_read_b128 v[194:197], v143 offset:36864
	ds_read_b128 v[198:201], v143 offset:37888
	ds_read_b128 v[208:211], v143 offset:38912
	ds_read_b128 v[212:215], v143 offset:39936
	global_load_lds_dwordx4 v[222:223], off
	v_lshl_add_u64 v[222:223], s[38:39], 0, v[132:133]
	s_mov_b32 m0, s23
	s_nop 0
	global_load_lds_dwordx4 v[222:223], off
	s_waitcnt vmcnt(8)
	s_waitcnt lgkmcnt(0)
	s_barrier
	s_waitcnt lgkmcnt(0)
	v_mfma_f32_16x16x32_bf16 v[124:127], v[146:149], v[178:181], v[124:127]
	v_mfma_f32_16x16x32_bf16 v[120:123], v[154:157], v[178:181], v[120:123]
	v_mfma_f32_16x16x32_bf16 v[108:111], v[146:149], v[186:189], v[108:111]
	v_mfma_f32_16x16x32_bf16 v[104:107], v[154:157], v[186:189], v[104:107]
	v_mfma_f32_16x16x32_bf16 v[92:95], v[146:149], v[194:197], v[92:95]
	v_mfma_f32_16x16x32_bf16 v[88:91], v[154:157], v[194:197], v[88:91]
	v_mfma_f32_16x16x32_bf16 v[76:79], v[146:149], v[208:211], v[76:79]
	v_mfma_f32_16x16x32_bf16 v[72:75], v[154:157], v[208:211], v[72:75]
	v_mfma_f32_16x16x32_bf16 v[124:127], v[150:153], v[182:185], v[124:127]
	v_mfma_f32_16x16x32_bf16 v[120:123], v[158:161], v[182:185], v[120:123]
	v_mfma_f32_16x16x32_bf16 v[108:111], v[150:153], v[190:193], v[108:111]
	v_mfma_f32_16x16x32_bf16 v[104:107], v[158:161], v[190:193], v[104:107]
	v_mfma_f32_16x16x32_bf16 v[92:95], v[150:153], v[198:201], v[92:95]
	v_mfma_f32_16x16x32_bf16 v[88:91], v[158:161], v[198:201], v[88:91]
	v_mfma_f32_16x16x32_bf16 v[76:79], v[150:153], v[212:215], v[76:79]
	v_mfma_f32_16x16x32_bf16 v[72:75], v[158:161], v[212:215], v[72:75]
	v_mfma_f32_16x16x32_bf16 v[116:119], v[162:165], v[178:181], v[116:119]
	v_mfma_f32_16x16x32_bf16 v[112:115], v[170:173], v[178:181], v[112:115]
	v_mfma_f32_16x16x32_bf16 v[100:103], v[162:165], v[186:189], v[100:103]
	v_mfma_f32_16x16x32_bf16 v[96:99], v[170:173], v[186:189], v[96:99]
	v_mfma_f32_16x16x32_bf16 v[84:87], v[162:165], v[194:197], v[84:87]
	v_mfma_f32_16x16x32_bf16 v[80:83], v[170:173], v[194:197], v[80:83]
	v_mfma_f32_16x16x32_bf16 v[68:71], v[162:165], v[208:211], v[68:71]
	v_mfma_f32_16x16x32_bf16 v[64:67], v[170:173], v[208:211], v[64:67]
	v_mfma_f32_16x16x32_bf16 v[116:119], v[166:169], v[182:185], v[116:119]
	v_mfma_f32_16x16x32_bf16 v[112:115], v[174:177], v[182:185], v[112:115]
	v_mfma_f32_16x16x32_bf16 v[100:103], v[166:169], v[190:193], v[100:103]
	v_mfma_f32_16x16x32_bf16 v[96:99], v[174:177], v[190:193], v[96:99]
	v_mfma_f32_16x16x32_bf16 v[84:87], v[166:169], v[198:201], v[84:87]
	v_mfma_f32_16x16x32_bf16 v[80:83], v[174:177], v[198:201], v[80:83]
	v_mfma_f32_16x16x32_bf16 v[68:71], v[166:169], v[212:215], v[68:71]
	v_mfma_f32_16x16x32_bf16 v[64:67], v[174:177], v[212:215], v[64:67]
	s_barrier
; #define PG8_STAGE(bufoff, gbase, voff) do { _Pragma("unroll") for (int _i = 0; _i < 2; ++_i) \
;         __builtin_amdgcn_global_load_lds((const unsigned*)((const char*)(gbase) + (voff)[_i]), (PG8_LAS unsigned*)(lds + (bufoff) + ldsw + _i * 8192), 16, 0, 0); } while (0)
; #define PG8_STAGE_NT(bufoff, gbase, voff) do { _Pragma("unroll") for (int _i = 0; _i < 2; ++_i) \
;         __builtin_amdgcn_global_load_lds((const unsigned*)((const char*)(gbase) + (voff)[_i]), (PG8_LAS unsigned*)(lds + (bufoff) + ldsw + _i * 8192), 16, 0, PG8_B_AUX); } while (0)
; #define PG8_LDA(dst, b, h) do { _Pragma("unroll") for (int m = 0; m < 4; ++m) _Pragma("unroll") for (int k = 0; k < 2; ++k) dst[m][k] = *(const PG8_LAS bf16x8*)(lds + PG8_SA(b, h) + aoff + m * 2048 + k * 1024); } while (0)
; #define PG8_MMA(ai, bj, At, Bt) do { __builtin_amdgcn_s_setprio(1); _Pragma("unroll") for (int m = 0; m < 4; ++m) _Pragma("unroll") for (int n = 0; n < 2; ++n) _Pragma("unroll") for (int k = 0; k < 2; ++k) \
;         acc[ai][bj][m][n] = __builtin_amdgcn_mfma_f32_16x16x32_bf16(Bt[n][k], At[m][k], acc[ai][bj][m][n], 0, 0, 0); __builtin_amdgcn_s_setprio(0); } while (0)
; #define PG8_WAIT_V(n) asm volatile("s_waitcnt vmcnt(" #n ")" ::: "memory")
; #define PG8_WAIT_L(n) asm volatile("s_waitcnt lgkmcnt(" #n ")" ::: "memory")
; #define PG8_BAR __builtin_amdgcn_s_barrier()
; #define PG8_SCHED __builtin_amdgcn_sched_barrier(0)
; template <class Epi, class Sched, bool ALIGN_EPI = false, bool SP2 = false>
; __device__ __forceinline__ void gemm_phase(PG8_LAS unsigned char* lds, const Gemm g, const Sched& S, const Epi& E, int wid) {
;     ...
;             PG8_LDA(At, 1, 1); PG8_STAGE_NT(PG8_SB(1, 0), b3, voffB); PG8_STAGE_NT(PG8_SB(1, 1), b3 + hstepB, voffB); PG8_STAGE(PG8_SA(1, 0), a3, voffA);
;             PG8_WAIT_V(8); PG8_WAIT_L(0); PG8_BAR; PG8_MMA(1, 0, At, B0); PG8_MMA(1, 1, At, B1); PG8_BAR; PG8_SCHED;
;     ...
;     PG8_WAIT_V(0);
;     if constexpr (!ALIGN_EPI) { if (wr == 0) PG8_BAR; }
	s_mov_b32 m0, s63
	v_lshl_add_u64 v[202:203], v[202:203], 0, s[4:5]
	s_add_u32 s30, s30, 0x2b4080
	ds_read_b128 v[178:181], v143 offset:49152
	ds_read_b128 v[182:185], v143 offset:50176
	ds_read_b128 v[186:189], v143 offset:51200
	ds_read_b128 v[190:193], v143 offset:52224
	ds_read_b128 v[194:197], v143 offset:53248
	ds_read_b128 v[198:201], v143 offset:54272
	ds_read_b128 v[208:211], v143 offset:55296
	ds_read_b128 v[212:215], v143 offset:56320
	global_load_lds_dwordx4 v[202:203], off
	v_lshl_add_u64 v[202:203], v[216:217], 0, s[4:5]
	s_mov_b32 m0, s64
	s_addc_u32 s31, s31, 0
	global_load_lds_dwordx4 v[202:203], off
	v_lshl_add_u64 v[202:203], s[30:31], 0, v[130:131]
	s_mov_b32 m0, s65
	s_nop 0
	global_load_lds_dwordx4 v[202:203], off
	v_lshl_add_u64 v[202:203], s[30:31], 0, v[134:135]
	s_mov_b32 m0, s66
	s_nop 0
	global_load_lds_dwordx4 v[202:203], off
	s_waitcnt vmcnt(4)
	s_waitcnt lgkmcnt(0)
	s_barrier
	s_waitcnt lgkmcnt(0)
	v_mfma_f32_16x16x32_bf16 v[60:63], v[146:149], v[178:181], v[60:63]
	v_mfma_f32_16x16x32_bf16 v[56:59], v[154:157], v[178:181], v[56:59]
	v_mfma_f32_16x16x32_bf16 v[44:47], v[146:149], v[186:189], v[44:47]
	v_mfma_f32_16x16x32_bf16 v[40:43], v[154:157], v[186:189], v[40:43]
	v_mfma_f32_16x16x32_bf16 v[28:31], v[146:149], v[194:197], v[28:31]
	v_mfma_f32_16x16x32_bf16 v[24:27], v[154:157], v[194:197], v[24:27]
	v_mfma_f32_16x16x32_bf16 v[12:15], v[146:149], v[208:211], v[12:15]
	v_mfma_f32_16x16x32_bf16 v[8:11], v[154:157], v[208:211], v[8:11]
	v_mfma_f32_16x16x32_bf16 v[60:63], v[150:153], v[182:185], v[60:63]
	v_mfma_f32_16x16x32_bf16 v[56:59], v[158:161], v[182:185], v[56:59]
	v_mfma_f32_16x16x32_bf16 v[44:47], v[150:153], v[190:193], v[44:47]
	v_mfma_f32_16x16x32_bf16 v[40:43], v[158:161], v[190:193], v[40:43]
	v_mfma_f32_16x16x32_bf16 v[28:31], v[150:153], v[198:201], v[28:31]
	v_mfma_f32_16x16x32_bf16 v[24:27], v[158:161], v[198:201], v[24:27]
	v_mfma_f32_16x16x32_bf16 v[12:15], v[150:153], v[212:215], v[12:15]
	v_mfma_f32_16x16x32_bf16 v[8:11], v[158:161], v[212:215], v[8:11]
	v_mfma_f32_16x16x32_bf16 v[52:55], v[162:165], v[178:181], v[52:55]
	v_mfma_f32_16x16x32_bf16 v[48:51], v[170:173], v[178:181], v[48:51]
	v_mfma_f32_16x16x32_bf16 v[36:39], v[162:165], v[186:189], v[36:39]
	v_mfma_f32_16x16x32_bf16 v[32:35], v[170:173], v[186:189], v[32:35]
	v_mfma_f32_16x16x32_bf16 v[20:23], v[162:165], v[194:197], v[20:23]
	v_mfma_f32_16x16x32_bf16 v[16:19], v[170:173], v[194:197], v[16:19]
	v_mfma_f32_16x16x32_bf16 v[4:7], v[162:165], v[208:211], v[4:7]
	v_mfma_f32_16x16x32_bf16 v[0:3], v[170:173], v[208:211], v[0:3]
	v_mfma_f32_16x16x32_bf16 v[52:55], v[166:169], v[182:185], v[52:55]
	v_mfma_f32_16x16x32_bf16 v[48:51], v[174:177], v[182:185], v[48:51]
	v_mfma_f32_16x16x32_bf16 v[36:39], v[166:169], v[190:193], v[36:39]
	v_mfma_f32_16x16x32_bf16 v[32:35], v[174:177], v[190:193], v[32:35]
	v_mfma_f32_16x16x32_bf16 v[20:23], v[166:169], v[198:201], v[20:23]
	v_mfma_f32_16x16x32_bf16 v[16:19], v[174:177], v[198:201], v[16:19]
	v_mfma_f32_16x16x32_bf16 v[4:7], v[166:169], v[212:215], v[4:7]
	v_mfma_f32_16x16x32_bf16 v[0:3], v[174:177], v[212:215], v[0:3]
	s_barrier
	s_add_i32 s41, s41, 2
	s_add_u32 s21, s21, 0x100
	s_addc_u32 s40, s40, 0
	s_add_u32 s8, s8, 0x100
	s_addc_u32 s9, s9, 0
	v_lshl_add_u64 v[136:137], v[136:137], 0, s[28:29]
	s_cmpk_lt_u32 s41, 0xaa
	v_lshl_add_u64 v[138:139], v[138:139], 0, s[28:29]
	s_cbranch_scc1 .LBB0_1307
	s_waitcnt vmcnt(0)
	s_andn2_b64 vcc, exec, s[44:45]
	s_cbranch_vccnz .LBB0_1310
	s_barrier
